# attention: softmax pass 1 (scale+bias+mask+max) of rows 0..5 issued under the S phase's fragment reads/MFMAs as well
# baseline (speedup 1.0000x reference)
.Latt_unit:
	s_waitcnt lgkmcnt(0)
	s_barrier
	v_mov_b32_e32 v251, 0xf149f2ca
	v_mov_b32_e32 v224, 0x3db504f3
	v_mov_b32_e32 v248, 0xff61b1e6
	global_load_dwordx4 v[4:7], v229, s[38:39] offset:0
	global_load_dwordx4 v[8:11], v230, s[38:39] offset:0
	global_load_dwordx4 v[12:15], v229, s[38:39] offset:128
	global_load_dwordx4 v[16:19], v230, s[38:39] offset:128
	global_load_dwordx4 v[20:23], v229, s[38:39] offset:256
	global_load_dwordx4 v[24:27], v230, s[38:39] offset:256
	global_load_dwordx4 v[28:31], v229, s[38:39] offset:384
	global_load_dwordx4 v[32:35], v230, s[38:39] offset:384
	global_load_dwordx4 v[36:39], v229, s[38:39] offset:512
	global_load_dwordx4 v[40:43], v230, s[38:39] offset:512
	global_load_dwordx4 v[44:47], v229, s[38:39] offset:640
	global_load_dwordx4 v[48:51], v230, s[38:39] offset:640
	global_load_dwordx4 v[52:55], v229, s[38:39] offset:768
	global_load_dwordx4 v[56:59], v230, s[38:39] offset:768
	s_add_i32 s30, s27, 0
	s_add_i32 s31, s30, -7
	s_cmp_lt_i32 s30, 7
	s_cselect_b32 s30, s30, s31
	s_mul_i32 s30, s30, 0x4800
	s_add_i32 s30, s30, 0x3c00
	v_add_u32_e32 v0, s30, v232
	ds_read_b128 v[156:159], v0 offset:0
	ds_read_b128 v[172:175], v0 offset:1088
	ds_read_b128 v[160:163], v0 offset:64
	ds_read_b128 v[176:179], v0 offset:1152
	ds_read_b128 v[164:167], v0 offset:128
	ds_read_b128 v[180:183], v0 offset:1216
	ds_read_b128 v[168:171], v0 offset:192
	ds_read_b128 v[184:187], v0 offset:1280
	s_waitcnt lgkmcnt(0)
	s_add_i32 s30, s27, 1
	s_add_i32 s31, s30, -7
	s_cmp_lt_i32 s30, 7
	s_cselect_b32 s30, s30, s31
	s_mul_i32 s30, s30, 0x4800
	s_add_i32 s30, s30, 0x3c00
	v_add_u32_e32 v0, s30, v232
	ds_read_b128 v[188:191], v0 offset:0
	ds_read_b128 v[204:207], v0 offset:1088
	ds_read_b128 v[192:195], v0 offset:64
	ds_read_b128 v[208:211], v0 offset:1152
	ds_read_b128 v[196:199], v0 offset:128
	ds_read_b128 v[212:215], v0 offset:1216
	ds_read_b128 v[200:203], v0 offset:192
	ds_read_b128 v[216:219], v0 offset:1280
	v_mfma_f32_16x16x32_bf16 v[92:95], v[156:159], v[76:79], 0
	v_mfma_f32_16x16x32_bf16 v[96:99], v[172:175], v[76:79], 0
	v_mfma_f32_16x16x32_bf16 v[92:95], v[160:163], v[80:83], v[92:95]
	v_mfma_f32_16x16x32_bf16 v[96:99], v[176:179], v[80:83], v[96:99]
	v_mfma_f32_16x16x32_bf16 v[92:95], v[164:167], v[84:87], v[92:95]
	v_mfma_f32_16x16x32_bf16 v[96:99], v[180:183], v[84:87], v[96:99]
	v_mfma_f32_16x16x32_bf16 v[92:95], v[168:171], v[88:91], v[92:95]
	v_mfma_f32_16x16x32_bf16 v[96:99], v[184:187], v[88:91], v[96:99]
	s_waitcnt lgkmcnt(0)
	s_add_i32 s30, s27, 2
	s_add_i32 s31, s30, -7
	s_cmp_lt_i32 s30, 7
	s_cselect_b32 s30, s30, s31
	s_mul_i32 s30, s30, 0x4800
	s_add_i32 s30, s30, 0x3c00
	v_add_u32_e32 v0, s30, v232
	ds_read_b128 v[156:159], v0 offset:0
	ds_read_b128 v[172:175], v0 offset:1088
	ds_read_b128 v[160:163], v0 offset:64
	ds_read_b128 v[176:179], v0 offset:1152
	ds_read_b128 v[164:167], v0 offset:128
	ds_read_b128 v[180:183], v0 offset:1216
	ds_read_b128 v[168:171], v0 offset:192
	ds_read_b128 v[184:187], v0 offset:1280
	v_add_u32_e32 v1, s67, v240
	ds_read_b32 v220, v1 offset:0
	v_add_u32_e32 v1, s67, v241
	ds_read_b32 v221, v1 offset:0
	v_add_u32_e32 v1, s67, v242
	ds_read_b32 v222, v1 offset:0
	v_add_u32_e32 v1, s67, v243
	ds_read_b32 v223, v1 offset:0
	v_add_u32_e32 v1, s67, v244
	ds_read_b32 v2, v1 offset:0
	v_add_u32_e32 v1, s67, v245
	ds_read_b32 v3, v1 offset:0
	v_add_u32_e32 v1, s67, v246
	ds_read_b32 v252, v1 offset:0
	v_add_u32_e32 v1, s67, v247
	ds_read_b32 v253, v1 offset:0
	v_mfma_f32_16x16x32_bf16 v[100:103], v[188:191], v[76:79], 0
	v_mfma_f32_16x16x32_bf16 v[104:107], v[204:207], v[76:79], 0
	v_mfma_f32_16x16x32_bf16 v[100:103], v[192:195], v[80:83], v[100:103]
	v_mfma_f32_16x16x32_bf16 v[104:107], v[208:211], v[80:83], v[104:107]
	v_mfma_f32_16x16x32_bf16 v[100:103], v[196:199], v[84:87], v[100:103]
	v_mfma_f32_16x16x32_bf16 v[104:107], v[212:215], v[84:87], v[104:107]
	v_mfma_f32_16x16x32_bf16 v[100:103], v[200:203], v[88:91], v[100:103]
	v_mfma_f32_16x16x32_bf16 v[104:107], v[216:219], v[88:91], v[104:107]
	s_waitcnt lgkmcnt(0)
	v_pk_fma_f32 v[92:93], v[92:93], v[224:225], v[220:221] op_sel_hi:[1,0,1]
	v_pk_fma_f32 v[94:95], v[94:95], v[224:225], v[222:223] op_sel_hi:[1,0,1]
	v_pk_fma_f32 v[96:97], v[96:97], v[224:225], v[2:3] op_sel_hi:[1,0,1]
	v_pk_fma_f32 v[98:99], v[98:99], v[224:225], v[252:253] op_sel_hi:[1,0,1]
	v_cndmask_b32_e64 v92, v251, v92, s[4:5]
	v_cndmask_b32_e64 v93, v251, v93, s[6:7]
	v_cndmask_b32_e64 v94, v251, v94, s[8:9]
	v_cndmask_b32_e64 v95, v251, v95, s[10:11]
	v_cndmask_b32_e64 v96, v251, v96, s[12:13]
	v_cndmask_b32_e64 v97, v251, v97, s[14:15]
	v_cndmask_b32_e64 v98, v251, v98, s[16:17]
	v_cndmask_b32_e64 v99, v251, v99, s[18:19]
	v_max3_f32 v248, v248, v92, v93
	v_max3_f32 v248, v248, v94, v95
	v_max3_f32 v248, v248, v96, v97
	v_max3_f32 v248, v248, v98, v99
	s_add_i32 s30, s27, 3
	s_add_i32 s31, s30, -7
	s_cmp_lt_i32 s30, 7
	s_cselect_b32 s30, s30, s31
	s_mul_i32 s30, s30, 0x4800
	s_add_i32 s30, s30, 0x3c00
	v_add_u32_e32 v0, s30, v232
	ds_read_b128 v[188:191], v0 offset:0
	ds_read_b128 v[204:207], v0 offset:1088
	ds_read_b128 v[192:195], v0 offset:64
	ds_read_b128 v[208:211], v0 offset:1152
	ds_read_b128 v[196:199], v0 offset:128
	ds_read_b128 v[212:215], v0 offset:1216
	ds_read_b128 v[200:203], v0 offset:192
	ds_read_b128 v[216:219], v0 offset:1280
	v_add_u32_e32 v1, s67, v240
	ds_read_b32 v220, v1 offset:124
	v_add_u32_e32 v1, s67, v241
	ds_read_b32 v221, v1 offset:124
	v_add_u32_e32 v1, s67, v242
	ds_read_b32 v222, v1 offset:124
	v_add_u32_e32 v1, s67, v243
	ds_read_b32 v223, v1 offset:124
	v_add_u32_e32 v1, s67, v244
	ds_read_b32 v2, v1 offset:124
	v_add_u32_e32 v1, s67, v245
	ds_read_b32 v3, v1 offset:124
	v_add_u32_e32 v1, s67, v246
	ds_read_b32 v252, v1 offset:124
	v_add_u32_e32 v1, s67, v247
	ds_read_b32 v253, v1 offset:124
	v_mfma_f32_16x16x32_bf16 v[108:111], v[156:159], v[76:79], 0
	v_mfma_f32_16x16x32_bf16 v[112:115], v[172:175], v[76:79], 0
	v_mfma_f32_16x16x32_bf16 v[108:111], v[160:163], v[80:83], v[108:111]
	v_mfma_f32_16x16x32_bf16 v[112:115], v[176:179], v[80:83], v[112:115]
	v_mfma_f32_16x16x32_bf16 v[108:111], v[164:167], v[84:87], v[108:111]
	v_mfma_f32_16x16x32_bf16 v[112:115], v[180:183], v[84:87], v[112:115]
	v_mfma_f32_16x16x32_bf16 v[108:111], v[168:171], v[88:91], v[108:111]
	v_mfma_f32_16x16x32_bf16 v[112:115], v[184:187], v[88:91], v[112:115]
	s_waitcnt lgkmcnt(0)
	v_pk_fma_f32 v[100:101], v[100:101], v[224:225], v[220:221] op_sel_hi:[1,0,1]
	v_pk_fma_f32 v[102:103], v[102:103], v[224:225], v[222:223] op_sel_hi:[1,0,1]
	v_pk_fma_f32 v[104:105], v[104:105], v[224:225], v[2:3] op_sel_hi:[1,0,1]
	v_pk_fma_f32 v[106:107], v[106:107], v[224:225], v[252:253] op_sel_hi:[1,0,1]
	v_cndmask_b32_e64 v100, v251, v100, s[4:5]
	v_cndmask_b32_e64 v101, v251, v101, s[6:7]
	v_cndmask_b32_e64 v102, v251, v102, s[8:9]
	v_cndmask_b32_e64 v103, v251, v103, s[10:11]
	v_cndmask_b32_e64 v104, v251, v104, s[12:13]
	v_cndmask_b32_e64 v105, v251, v105, s[14:15]
	v_cndmask_b32_e64 v106, v251, v106, s[16:17]
	v_cndmask_b32_e64 v107, v251, v107, s[18:19]
	v_max3_f32 v248, v248, v100, v101
	v_max3_f32 v248, v248, v102, v103
	v_max3_f32 v248, v248, v104, v105
	v_max3_f32 v248, v248, v106, v107
	s_add_i32 s30, s27, 4
	s_add_i32 s31, s30, -7
	s_cmp_lt_i32 s30, 7
	s_cselect_b32 s30, s30, s31
	s_mul_i32 s30, s30, 0x4800
	s_add_i32 s30, s30, 0x3c00
	v_add_u32_e32 v0, s30, v232
	ds_read_b128 v[156:159], v0 offset:0
	ds_read_b128 v[172:175], v0 offset:1088
	ds_read_b128 v[160:163], v0 offset:64
	ds_read_b128 v[176:179], v0 offset:1152
	ds_read_b128 v[164:167], v0 offset:128
	ds_read_b128 v[180:183], v0 offset:1216
	ds_read_b128 v[168:171], v0 offset:192
	ds_read_b128 v[184:187], v0 offset:1280
	v_add_u32_e32 v1, s67, v240
	ds_read_b32 v220, v1 offset:248
	v_add_u32_e32 v1, s67, v241
	ds_read_b32 v221, v1 offset:248
	v_add_u32_e32 v1, s67, v242
	ds_read_b32 v222, v1 offset:248
	v_add_u32_e32 v1, s67, v243
	ds_read_b32 v223, v1 offset:248
	v_add_u32_e32 v1, s67, v244
	ds_read_b32 v2, v1 offset:248
	v_add_u32_e32 v1, s67, v245
	ds_read_b32 v3, v1 offset:248
	v_add_u32_e32 v1, s67, v246
	ds_read_b32 v252, v1 offset:248
	v_add_u32_e32 v1, s67, v247
	ds_read_b32 v253, v1 offset:248
	v_mfma_f32_16x16x32_bf16 v[116:119], v[188:191], v[76:79], 0
	v_mfma_f32_16x16x32_bf16 v[120:123], v[204:207], v[76:79], 0
	v_mfma_f32_16x16x32_bf16 v[116:119], v[192:195], v[80:83], v[116:119]
	v_mfma_f32_16x16x32_bf16 v[120:123], v[208:211], v[80:83], v[120:123]
	v_mfma_f32_16x16x32_bf16 v[116:119], v[196:199], v[84:87], v[116:119]
	v_mfma_f32_16x16x32_bf16 v[120:123], v[212:215], v[84:87], v[120:123]
	v_mfma_f32_16x16x32_bf16 v[116:119], v[200:203], v[88:91], v[116:119]
	v_mfma_f32_16x16x32_bf16 v[120:123], v[216:219], v[88:91], v[120:123]
	s_waitcnt lgkmcnt(0)
	v_pk_fma_f32 v[108:109], v[108:109], v[224:225], v[220:221] op_sel_hi:[1,0,1]
	v_pk_fma_f32 v[110:111], v[110:111], v[224:225], v[222:223] op_sel_hi:[1,0,1]
	v_pk_fma_f32 v[112:113], v[112:113], v[224:225], v[2:3] op_sel_hi:[1,0,1]
	v_pk_fma_f32 v[114:115], v[114:115], v[224:225], v[252:253] op_sel_hi:[1,0,1]
	v_cndmask_b32_e64 v108, v251, v108, s[4:5]
	v_cndmask_b32_e64 v109, v251, v109, s[6:7]
	v_cndmask_b32_e64 v110, v251, v110, s[8:9]
	v_cndmask_b32_e64 v111, v251, v111, s[10:11]
	v_cndmask_b32_e64 v112, v251, v112, s[12:13]
	v_cndmask_b32_e64 v113, v251, v113, s[14:15]
	v_cndmask_b32_e64 v114, v251, v114, s[16:17]
	v_cndmask_b32_e64 v115, v251, v115, s[18:19]
	v_max3_f32 v248, v248, v108, v109
	v_max3_f32 v248, v248, v110, v111
	v_max3_f32 v248, v248, v112, v113
	v_max3_f32 v248, v248, v114, v115
	s_add_i32 s30, s27, 5
	s_add_i32 s31, s30, -7
	s_cmp_lt_i32 s30, 7
	s_cselect_b32 s30, s30, s31
	s_mul_i32 s30, s30, 0x4800
	s_add_i32 s30, s30, 0x3c00
	v_add_u32_e32 v0, s30, v232
	ds_read_b128 v[188:191], v0 offset:0
	ds_read_b128 v[204:207], v0 offset:1088
	ds_read_b128 v[192:195], v0 offset:64
	ds_read_b128 v[208:211], v0 offset:1152
	ds_read_b128 v[196:199], v0 offset:128
	ds_read_b128 v[212:215], v0 offset:1216
	ds_read_b128 v[200:203], v0 offset:192
	ds_read_b128 v[216:219], v0 offset:1280
	v_add_u32_e32 v1, s67, v240
	ds_read_b32 v220, v1 offset:372
	v_add_u32_e32 v1, s67, v241
	ds_read_b32 v221, v1 offset:372
	v_add_u32_e32 v1, s67, v242
	ds_read_b32 v222, v1 offset:372
	v_add_u32_e32 v1, s67, v243
	ds_read_b32 v223, v1 offset:372
	v_add_u32_e32 v1, s67, v244
	ds_read_b32 v2, v1 offset:372
	v_add_u32_e32 v1, s67, v245
	ds_read_b32 v3, v1 offset:372
	v_add_u32_e32 v1, s67, v246
	ds_read_b32 v252, v1 offset:372
	v_add_u32_e32 v1, s67, v247
	ds_read_b32 v253, v1 offset:372
	v_mfma_f32_16x16x32_bf16 v[124:127], v[156:159], v[76:79], 0
	v_mfma_f32_16x16x32_bf16 v[128:131], v[172:175], v[76:79], 0
	v_mfma_f32_16x16x32_bf16 v[124:127], v[160:163], v[80:83], v[124:127]
	v_mfma_f32_16x16x32_bf16 v[128:131], v[176:179], v[80:83], v[128:131]
	v_mfma_f32_16x16x32_bf16 v[124:127], v[164:167], v[84:87], v[124:127]
	v_mfma_f32_16x16x32_bf16 v[128:131], v[180:183], v[84:87], v[128:131]
	v_mfma_f32_16x16x32_bf16 v[124:127], v[168:171], v[88:91], v[124:127]
	v_mfma_f32_16x16x32_bf16 v[128:131], v[184:187], v[88:91], v[128:131]
	s_waitcnt lgkmcnt(0)
	v_pk_fma_f32 v[116:117], v[116:117], v[224:225], v[220:221] op_sel_hi:[1,0,1]
	v_pk_fma_f32 v[118:119], v[118:119], v[224:225], v[222:223] op_sel_hi:[1,0,1]
	v_pk_fma_f32 v[120:121], v[120:121], v[224:225], v[2:3] op_sel_hi:[1,0,1]
	v_pk_fma_f32 v[122:123], v[122:123], v[224:225], v[252:253] op_sel_hi:[1,0,1]
	v_cndmask_b32_e64 v116, v251, v116, s[4:5]
	v_cndmask_b32_e64 v117, v251, v117, s[6:7]
	v_cndmask_b32_e64 v118, v251, v118, s[8:9]
	v_cndmask_b32_e64 v119, v251, v119, s[10:11]
	v_cndmask_b32_e64 v120, v251, v120, s[12:13]
	v_cndmask_b32_e64 v121, v251, v121, s[14:15]
	v_cndmask_b32_e64 v122, v251, v122, s[16:17]
	v_cndmask_b32_e64 v123, v251, v123, s[18:19]
	v_max3_f32 v248, v248, v116, v117
	v_max3_f32 v248, v248, v118, v119
	v_max3_f32 v248, v248, v120, v121
	v_max3_f32 v248, v248, v122, v123
	s_cmp_lg_u32 s27, 0
	s_cbranch_scc1 .Latt_s6a_skip
	s_add_i32 s30, s27, 6
	s_add_i32 s31, s30, -7
	s_cmp_lt_i32 s30, 7
	s_cselect_b32 s30, s30, s31
	s_mul_i32 s30, s30, 0x4800
	s_add_i32 s30, s30, 0x3c00
	v_add_u32_e32 v0, s30, v232
	ds_read_b128 v[156:159], v0 offset:0
	ds_read_b128 v[172:175], v0 offset:1088
	ds_read_b128 v[160:163], v0 offset:64
	ds_read_b128 v[176:179], v0 offset:1152
	ds_read_b128 v[164:167], v0 offset:128
	ds_read_b128 v[180:183], v0 offset:1216
	ds_read_b128 v[168:171], v0 offset:192
	ds_read_b128 v[184:187], v0 offset:1280
	v_mfma_f32_16x16x32_bf16 v[132:135], v[188:191], v[76:79], 0
	v_mfma_f32_16x16x32_bf16 v[136:139], v[204:207], v[76:79], 0
	v_mfma_f32_16x16x32_bf16 v[132:135], v[192:195], v[80:83], v[132:135]
	v_mfma_f32_16x16x32_bf16 v[136:139], v[208:211], v[80:83], v[136:139]
	v_mfma_f32_16x16x32_bf16 v[132:135], v[196:199], v[84:87], v[132:135]
	v_mfma_f32_16x16x32_bf16 v[136:139], v[212:215], v[84:87], v[136:139]
	v_mfma_f32_16x16x32_bf16 v[132:135], v[200:203], v[88:91], v[132:135]
	v_mfma_f32_16x16x32_bf16 v[136:139], v[216:219], v[88:91], v[136:139]
	s_waitcnt lgkmcnt(0)
	v_mfma_f32_16x16x32_bf16 v[140:143], v[156:159], v[76:79], 0
	v_mfma_f32_16x16x32_bf16 v[144:147], v[172:175], v[76:79], 0
	v_mfma_f32_16x16x32_bf16 v[140:143], v[160:163], v[80:83], v[140:143]
	v_mfma_f32_16x16x32_bf16 v[144:147], v[176:179], v[80:83], v[144:147]
	v_mfma_f32_16x16x32_bf16 v[140:143], v[164:167], v[84:87], v[140:143]
	v_mfma_f32_16x16x32_bf16 v[144:147], v[180:183], v[84:87], v[144:147]
	v_mfma_f32_16x16x32_bf16 v[140:143], v[168:171], v[88:91], v[140:143]
	v_mfma_f32_16x16x32_bf16 v[144:147], v[184:187], v[88:91], v[144:147]
	s_branch .Latt_s6a_done

.Latt_v8_skip:
	s_cmp_eq_u32 s27, 0
	s_cbranch_scc1 .Latt_s6b_skip
	v_add_u32_e32 v1, s67, v240
	ds_read_b32 v220, v1 offset:496
	v_add_u32_e32 v1, s67, v241
	ds_read_b32 v221, v1 offset:496
	v_add_u32_e32 v1, s67, v242
	ds_read_b32 v222, v1 offset:496
	v_add_u32_e32 v1, s67, v243
	ds_read_b32 v223, v1 offset:496
	v_add_u32_e32 v1, s67, v244
	ds_read_b32 v2, v1 offset:496
	v_add_u32_e32 v1, s67, v245
	ds_read_b32 v3, v1 offset:496
	v_add_u32_e32 v1, s67, v246
	ds_read_b32 v252, v1 offset:496
	v_add_u32_e32 v1, s67, v247
	ds_read_b32 v253, v1 offset:496
	s_add_i32 s30, s27, 6
	s_add_i32 s31, s30, -7
	s_cmp_lt_i32 s30, 7
	s_cselect_b32 s30, s30, s31
	s_mul_i32 s30, s30, 0x4800
	s_add_i32 s30, s30, 0x3c00
	v_add_u32_e32 v0, s30, v232
	ds_read_b128 v[156:159], v0 offset:0
	ds_read_b128 v[172:175], v0 offset:1088
	ds_read_b128 v[160:163], v0 offset:64
	ds_read_b128 v[176:179], v0 offset:1152
	ds_read_b128 v[164:167], v0 offset:128
	ds_read_b128 v[180:183], v0 offset:1216
	ds_read_b128 v[168:171], v0 offset:192
	ds_read_b128 v[184:187], v0 offset:1280
	s_waitcnt lgkmcnt(0)
	v_pk_fma_f32 v[124:125], v[124:125], v[224:225], v[220:221] op_sel_hi:[1,0,1]
	v_pk_fma_f32 v[126:127], v[126:127], v[224:225], v[222:223] op_sel_hi:[1,0,1]
	v_pk_fma_f32 v[128:129], v[128:129], v[224:225], v[2:3] op_sel_hi:[1,0,1]
	v_pk_fma_f32 v[130:131], v[130:131], v[224:225], v[252:253] op_sel_hi:[1,0,1]
	v_cndmask_b32_e64 v124, v251, v124, s[4:5]
	v_cndmask_b32_e64 v125, v251, v125, s[6:7]
	v_cndmask_b32_e64 v126, v251, v126, s[8:9]
	v_cndmask_b32_e64 v127, v251, v127, s[10:11]
	v_cndmask_b32_e64 v128, v251, v128, s[12:13]
	v_cndmask_b32_e64 v129, v251, v129, s[14:15]
	v_cndmask_b32_e64 v130, v251, v130, s[16:17]
	v_cndmask_b32_e64 v131, v251, v131, s[18:19]
	v_max3_f32 v248, v248, v124, v125
	v_max3_f32 v248, v248, v126, v127
	v_max3_f32 v248, v248, v128, v129
	v_max3_f32 v248, v248, v130, v131
	v_add_u32_e32 v1, s67, v240
	ds_read_b32 v220, v1 offset:620
	v_add_u32_e32 v1, s67, v241
	ds_read_b32 v221, v1 offset:620
	v_add_u32_e32 v1, s67, v242
	ds_read_b32 v222, v1 offset:620
	v_add_u32_e32 v1, s67, v243
	ds_read_b32 v223, v1 offset:620
	v_add_u32_e32 v1, s67, v244
	ds_read_b32 v2, v1 offset:620
	v_add_u32_e32 v1, s67, v245
	ds_read_b32 v3, v1 offset:620
	v_add_u32_e32 v1, s67, v246
	ds_read_b32 v252, v1 offset:620
	v_add_u32_e32 v1, s67, v247
	ds_read_b32 v253, v1 offset:620
	s_add_i32 s30, s27, 7
	s_add_i32 s31, s30, -7
	s_cmp_lt_i32 s30, 7
	s_cselect_b32 s30, s30, s31
	s_mul_i32 s30, s30, 0x4800
	s_add_i32 s30, s30, 0x3c00
	v_add_u32_e32 v0, s30, v232
	ds_read_b128 v[188:191], v0 offset:0
	ds_read_b128 v[204:207], v0 offset:1088
	ds_read_b128 v[192:195], v0 offset:64
	ds_read_b128 v[208:211], v0 offset:1152
	ds_read_b128 v[196:199], v0 offset:128
	ds_read_b128 v[212:215], v0 offset:1216
	ds_read_b128 v[200:203], v0 offset:192
	ds_read_b128 v[216:219], v0 offset:1280
	v_mfma_f32_16x16x32_bf16 v[140:143], v[156:159], v[76:79], 0
	v_mfma_f32_16x16x32_bf16 v[144:147], v[172:175], v[76:79], 0
	v_mfma_f32_16x16x32_bf16 v[140:143], v[160:163], v[80:83], v[140:143]
	v_mfma_f32_16x16x32_bf16 v[144:147], v[176:179], v[80:83], v[144:147]
	v_mfma_f32_16x16x32_bf16 v[140:143], v[164:167], v[84:87], v[140:143]
	v_mfma_f32_16x16x32_bf16 v[144:147], v[180:183], v[84:87], v[144:147]
	v_mfma_f32_16x16x32_bf16 v[140:143], v[168:171], v[88:91], v[140:143]
	v_mfma_f32_16x16x32_bf16 v[144:147], v[184:187], v[88:91], v[144:147]
	s_waitcnt lgkmcnt(0)
	v_pk_fma_f32 v[132:133], v[132:133], v[224:225], v[220:221] op_sel_hi:[1,0,1]
	v_pk_fma_f32 v[134:135], v[134:135], v[224:225], v[222:223] op_sel_hi:[1,0,1]
	v_pk_fma_f32 v[136:137], v[136:137], v[224:225], v[2:3] op_sel_hi:[1,0,1]
	v_pk_fma_f32 v[138:139], v[138:139], v[224:225], v[252:253] op_sel_hi:[1,0,1]
	v_cndmask_b32_e64 v132, v251, v132, s[4:5]
	v_cndmask_b32_e64 v133, v251, v133, s[6:7]
	v_cndmask_b32_e64 v134, v251, v134, s[8:9]
	v_cndmask_b32_e64 v135, v251, v135, s[10:11]
	v_cndmask_b32_e64 v136, v251, v136, s[12:13]
	v_cndmask_b32_e64 v137, v251, v137, s[14:15]
	v_cndmask_b32_e64 v138, v251, v138, s[16:17]
	v_cndmask_b32_e64 v139, v251, v139, s[18:19]
	v_max3_f32 v248, v248, v132, v133
	v_max3_f32 v248, v248, v134, v135
	v_max3_f32 v248, v248, v136, v137
	v_max3_f32 v248, v248, v138, v139
	v_mfma_f32_16x16x32_bf16 v[148:151], v[188:191], v[76:79], 0
	v_mfma_f32_16x16x32_bf16 v[152:155], v[204:207], v[76:79], 0
	v_mfma_f32_16x16x32_bf16 v[148:151], v[192:195], v[80:83], v[148:151]
	v_mfma_f32_16x16x32_bf16 v[152:155], v[208:211], v[80:83], v[152:155]
	v_mfma_f32_16x16x32_bf16 v[148:151], v[196:199], v[84:87], v[148:151]
	v_mfma_f32_16x16x32_bf16 v[152:155], v[212:215], v[84:87], v[152:155]
	v_mfma_f32_16x16x32_bf16 v[148:151], v[200:203], v[88:91], v[148:151]
	v_mfma_f32_16x16x32_bf16 v[152:155], v[216:219], v[88:91], v[152:155]
	s_branch .Latt_s6b_done
.Latt_s6b_skip:
	v_add_u32_e32 v1, s67, v240
	ds_read_b32 v220, v1 offset:496
	v_add_u32_e32 v1, s67, v241
	ds_read_b32 v221, v1 offset:496
	v_add_u32_e32 v1, s67, v242
	ds_read_b32 v222, v1 offset:496
	v_add_u32_e32 v1, s67, v243
	ds_read_b32 v223, v1 offset:496
	v_add_u32_e32 v1, s67, v244
	ds_read_b32 v2, v1 offset:496
	v_add_u32_e32 v1, s67, v245
	ds_read_b32 v3, v1 offset:496
	v_add_u32_e32 v1, s67, v246
	ds_read_b32 v252, v1 offset:496
	v_add_u32_e32 v1, s67, v247
	ds_read_b32 v253, v1 offset:496
	s_add_i32 s30, s27, 7
	s_add_i32 s31, s30, -7
	s_cmp_lt_i32 s30, 7
	s_cselect_b32 s30, s30, s31
	s_mul_i32 s30, s30, 0x4800
	s_add_i32 s30, s30, 0x3c00
	v_add_u32_e32 v0, s30, v232
	ds_read_b128 v[188:191], v0 offset:0
	ds_read_b128 v[204:207], v0 offset:1088
	ds_read_b128 v[192:195], v0 offset:64
	ds_read_b128 v[208:211], v0 offset:1152
	ds_read_b128 v[196:199], v0 offset:128
	ds_read_b128 v[212:215], v0 offset:1216
	ds_read_b128 v[200:203], v0 offset:192
	ds_read_b128 v[216:219], v0 offset:1280
	s_waitcnt lgkmcnt(0)
	v_pk_fma_f32 v[124:125], v[124:125], v[224:225], v[220:221] op_sel_hi:[1,0,1]
	v_pk_fma_f32 v[126:127], v[126:127], v[224:225], v[222:223] op_sel_hi:[1,0,1]
	v_pk_fma_f32 v[128:129], v[128:129], v[224:225], v[2:3] op_sel_hi:[1,0,1]
	v_pk_fma_f32 v[130:131], v[130:131], v[224:225], v[252:253] op_sel_hi:[1,0,1]
	v_cndmask_b32_e64 v124, v251, v124, s[4:5]
	v_cndmask_b32_e64 v125, v251, v125, s[6:7]
	v_cndmask_b32_e64 v126, v251, v126, s[8:9]
	v_cndmask_b32_e64 v127, v251, v127, s[10:11]
	v_cndmask_b32_e64 v128, v251, v128, s[12:13]
	v_cndmask_b32_e64 v129, v251, v129, s[14:15]
	v_cndmask_b32_e64 v130, v251, v130, s[16:17]
	v_cndmask_b32_e64 v131, v251, v131, s[18:19]
	v_max3_f32 v248, v248, v124, v125
	v_max3_f32 v248, v248, v126, v127
	v_max3_f32 v248, v248, v128, v129
	v_max3_f32 v248, v248, v130, v131
	v_add_u32_e32 v1, s67, v240
	ds_read_b32 v220, v1 offset:620
	v_add_u32_e32 v1, s67, v241
	ds_read_b32 v221, v1 offset:620
	v_add_u32_e32 v1, s67, v242
	ds_read_b32 v222, v1 offset:620
	v_add_u32_e32 v1, s67, v243
	ds_read_b32 v223, v1 offset:620
	v_add_u32_e32 v1, s67, v244
	ds_read_b32 v2, v1 offset:620
	v_add_u32_e32 v1, s67, v245
	ds_read_b32 v3, v1 offset:620
	v_add_u32_e32 v1, s67, v246
	ds_read_b32 v252, v1 offset:620
	v_add_u32_e32 v1, s67, v247
	ds_read_b32 v253, v1 offset:620
	v_mfma_f32_16x16x32_bf16 v[148:151], v[188:191], v[76:79], 0
	v_mfma_f32_16x16x32_bf16 v[152:155], v[204:207], v[76:79], 0
	v_mfma_f32_16x16x32_bf16 v[148:151], v[192:195], v[80:83], v[148:151]
	v_mfma_f32_16x16x32_bf16 v[152:155], v[208:211], v[80:83], v[152:155]
	v_mfma_f32_16x16x32_bf16 v[148:151], v[196:199], v[84:87], v[148:151]
	v_mfma_f32_16x16x32_bf16 v[152:155], v[212:215], v[84:87], v[152:155]
	v_mfma_f32_16x16x32_bf16 v[148:151], v[200:203], v[88:91], v[148:151]
	v_mfma_f32_16x16x32_bf16 v[152:155], v[216:219], v[88:91], v[152:155]
	s_waitcnt lgkmcnt(0)
	v_pk_fma_f32 v[132:133], v[132:133], v[224:225], v[220:221] op_sel_hi:[1,0,1]
	v_pk_fma_f32 v[134:135], v[134:135], v[224:225], v[222:223] op_sel_hi:[1,0,1]
	v_pk_fma_f32 v[136:137], v[136:137], v[224:225], v[2:3] op_sel_hi:[1,0,1]
	v_pk_fma_f32 v[138:139], v[138:139], v[224:225], v[252:253] op_sel_hi:[1,0,1]
	v_cndmask_b32_e64 v132, v251, v132, s[4:5]
	v_cndmask_b32_e64 v133, v251, v133, s[6:7]
	v_cndmask_b32_e64 v134, v251, v134, s[8:9]
	v_cndmask_b32_e64 v135, v251, v135, s[10:11]
	v_cndmask_b32_e64 v136, v251, v136, s[12:13]
	v_cndmask_b32_e64 v137, v251, v137, s[14:15]
	v_cndmask_b32_e64 v138, v251, v138, s[16:17]
	v_cndmask_b32_e64 v139, v251, v139, s[18:19]
	v_max3_f32 v248, v248, v132, v133
	v_max3_f32 v248, v248, v134, v135
	v_max3_f32 v248, v248, v136, v137
	v_max3_f32 v248, v248, v138, v139

.Latt_vw_go:
	v_add_u32_e32 v0, 0x3c00, v231
	ds_write_b128 v0, v[4:7]
	ds_write_b128 v0, v[8:11] offset:9216
	v_add_u32_e32 v0, 0x8400, v231
	ds_write_b128 v0, v[12:15]
	ds_write_b128 v0, v[16:19] offset:9216
	v_add_u32_e32 v0, 0xcc00, v231
	ds_write_b128 v0, v[20:23]
	ds_write_b128 v0, v[24:27] offset:9216
	v_add_u32_e32 v0, 0x11400, v231
	ds_write_b128 v0, v[28:31]
	ds_write_b128 v0, v[32:35] offset:9216
	v_add_u32_e32 v0, 0x15c00, v231
	ds_write_b128 v0, v[36:39]
	ds_write_b128 v0, v[40:43] offset:9216
	v_add_u32_e32 v0, 0x1a400, v231
	ds_write_b128 v0, v[44:47]
	ds_write_b128 v0, v[48:51] offset:9216
	v_add_u32_e32 v0, 0x1ec00, v231
	ds_write_b128 v0, v[52:55]
	ds_write_b128 v0, v[56:59] offset:9216
	v_mov_b32_e32 v254, 0x3fb8aa3b
	v_add_u32_e32 v1, s67, v240
	ds_read_b32 v220, v1 offset:744
	v_add_u32_e32 v1, s67, v241
	ds_read_b32 v221, v1 offset:744
	v_add_u32_e32 v1, s67, v242
	ds_read_b32 v222, v1 offset:744
	v_add_u32_e32 v1, s67, v243
	ds_read_b32 v223, v1 offset:744
	v_add_u32_e32 v1, s67, v244
	ds_read_b32 v2, v1 offset:744
	v_add_u32_e32 v1, s67, v245
	ds_read_b32 v3, v1 offset:744
	v_add_u32_e32 v1, s67, v246
	ds_read_b32 v252, v1 offset:744
	v_add_u32_e32 v1, s67, v247
	ds_read_b32 v253, v1 offset:744
	s_waitcnt lgkmcnt(0)
	v_pk_fma_f32 v[140:141], v[140:141], v[224:225], v[220:221] op_sel_hi:[1,0,1]
	v_pk_fma_f32 v[142:143], v[142:143], v[224:225], v[222:223] op_sel_hi:[1,0,1]
	v_pk_fma_f32 v[144:145], v[144:145], v[224:225], v[2:3] op_sel_hi:[1,0,1]
	v_pk_fma_f32 v[146:147], v[146:147], v[224:225], v[252:253] op_sel_hi:[1,0,1]
	v_cndmask_b32_e64 v140, v251, v140, s[4:5]
	v_cndmask_b32_e64 v141, v251, v141, s[6:7]
	v_cndmask_b32_e64 v142, v251, v142, s[8:9]
	v_cndmask_b32_e64 v143, v251, v143, s[10:11]
	v_cndmask_b32_e64 v144, v251, v144, s[12:13]
	v_cndmask_b32_e64 v145, v251, v145, s[14:15]
	v_cndmask_b32_e64 v146, v251, v146, s[16:17]
	v_cndmask_b32_e64 v147, v251, v147, s[18:19]
	v_max3_f32 v248, v248, v140, v141
	v_max3_f32 v248, v248, v142, v143
	v_max3_f32 v248, v248, v144, v145
	v_max3_f32 v248, v248, v146, v147
	v_add_u32_e32 v1, s67, v240
	ds_read_b32 v220, v1 offset:868
	v_add_u32_e32 v1, s67, v241
	ds_read_b32 v221, v1 offset:868
	v_add_u32_e32 v1, s67, v242
	ds_read_b32 v222, v1 offset:868
	v_add_u32_e32 v1, s67, v243
	ds_read_b32 v223, v1 offset:868
	v_add_u32_e32 v1, s67, v244
	ds_read_b32 v2, v1 offset:868
	v_add_u32_e32 v1, s67, v245
	ds_read_b32 v3, v1 offset:868
	v_add_u32_e32 v1, s67, v246
	ds_read_b32 v252, v1 offset:868
	v_add_u32_e32 v1, s67, v247
	ds_read_b32 v253, v1 offset:868
	s_waitcnt lgkmcnt(0)
	v_pk_fma_f32 v[148:149], v[148:149], v[224:225], v[220:221] op_sel_hi:[1,0,1]
	v_pk_fma_f32 v[150:151], v[150:151], v[224:225], v[222:223] op_sel_hi:[1,0,1]
	v_pk_fma_f32 v[152:153], v[152:153], v[224:225], v[2:3] op_sel_hi:[1,0,1]
	v_pk_fma_f32 v[154:155], v[154:155], v[224:225], v[252:253] op_sel_hi:[1,0,1]
	v_cndmask_b32_e64 v148, v251, v148, s[4:5]
	v_cndmask_b32_e64 v149, v251, v149, s[6:7]
	v_cndmask_b32_e64 v150, v251, v150, s[8:9]
	v_cndmask_b32_e64 v151, v251, v151, s[10:11]
	v_cndmask_b32_e64 v152, v251, v152, s[12:13]
	v_cndmask_b32_e64 v153, v251, v153, s[14:15]
	v_cndmask_b32_e64 v154, v251, v154, s[16:17]
	v_cndmask_b32_e64 v155, v251, v155, s[18:19]
	v_max3_f32 v248, v248, v148, v149
	v_max3_f32 v248, v248, v150, v151
	v_max3_f32 v248, v248, v152, v153
	v_max3_f32 v248, v248, v154, v155
	ds_bpermute_b32 v0, v238, v248
	s_waitcnt lgkmcnt(0)
	v_max_f32_e32 v248, v248, v0
	ds_bpermute_b32 v0, v239, v248
	s_waitcnt lgkmcnt(0)
	v_max_f32_e32 v248, v248, v0
	v_mov_b32_e32 v2, 0
	v_mov_b32_e32 v3, 0
	v_pk_add_f32 v[92:93], v[92:93], v[248:249] op_sel_hi:[1,0] neg_lo:[0,1] neg_hi:[0,1]
	v_pk_add_f32 v[94:95], v[94:95], v[248:249] op_sel_hi:[1,0] neg_lo:[0,1] neg_hi:[0,1]
	v_pk_add_f32 v[96:97], v[96:97], v[248:249] op_sel_hi:[1,0] neg_lo:[0,1] neg_hi:[0,1]
	v_pk_add_f32 v[98:99], v[98:99], v[248:249] op_sel_hi:[1,0] neg_lo:[0,1] neg_hi:[0,1]
	v_pk_mul_f32 v[92:93], v[92:93], v[254:255] op_sel_hi:[1,0]
	v_pk_mul_f32 v[94:95], v[94:95], v[254:255] op_sel_hi:[1,0]
	v_pk_mul_f32 v[96:97], v[96:97], v[254:255] op_sel_hi:[1,0]
	v_pk_mul_f32 v[98:99], v[98:99], v[254:255] op_sel_hi:[1,0]
	v_exp_f32_e32 v92, v92
	v_exp_f32_e32 v93, v93
	v_exp_f32_e32 v94, v94
	v_exp_f32_e32 v95, v95
	v_exp_f32_e32 v96, v96
	v_exp_f32_e32 v97, v97
	v_exp_f32_e32 v98, v98
	v_exp_f32_e32 v99, v99
	s_nop 0
	v_pk_add_f32 v[2:3], v[2:3], v[92:93]
	v_pk_add_f32 v[2:3], v[2:3], v[94:95]
	v_pk_add_f32 v[2:3], v[2:3], v[96:97]
	v_pk_add_f32 v[2:3], v[2:3], v[98:99]
	s_barrier
	s_add_i32 s30, s20, s46
	s_cmpk_lt_i32 s30, 0x200
	s_cbranch_scc0 .Latt_nopf1
	s_and_b32 s69, s30, 7
	s_lshr_b32 s76, s30, 8
	s_lshl_b32 s69, s69, 1
	s_add_i32 s69, s69, s76
	s_lshl_b32 s69, s69, 12
	s_bfe_u32 s76, s30, 0x50003
	s_lshl_b32 s76, s76, 1
	s_add_i32 s77, s76, -4
	s_max_i32 s77, s77, 0
	s_min_i32 s77, s77, 56
	s_add_i32 s83, s76, -3
	s_max_i32 s83, s83, 0
	s_min_i32 s83, s83, 56
	s_add_i32 s83, s83, 8
	s_sub_i32 s83, s83, s77
	s_add_i32 s76, s76, s88
	s_lshl_b32 s77, s77, 6
	s_add_i32 s77, s77, s69
	s_lshl_b32 s77, s77, 8
	s_add_u32 s34, s50, s77
	s_addc_u32 s35, s51, 0
	s_add_u32 s34, s34, 0xe200000
	s_addc_u32 s35, s35, 0
	s_lshl_b32 s76, s76, 6
	s_add_i32 s76, s76, s69
	s_lshl_b32 s77, s92, 4
	s_add_i32 s76, s76, s77
	s_lshl_b32 s76, s76, 8
	s_add_u32 s36, s50, s76
	s_addc_u32 s37, s51, 0
	s_add_u32 s36, s36, 0xd200000
	s_addc_u32 s37, s37, 0
	global_load_dwordx4 v[76:79], v235, s[36:37] offset:0
	global_load_dwordx4 v[80:83], v235, s[36:37] offset:64
	global_load_dwordx4 v[84:87], v235, s[36:37] offset:128
	global_load_dwordx4 v[88:91], v235, s[36:37] offset:192
	global_load_dwordx4 v[4:7], v226, s[34:35]
	global_load_dwordx4 v[8:11], v227, s[34:35]
	s_add_u32 s34, s34, 0x4000
	s_addc_u32 s35, s35, 0
	global_load_dwordx4 v[12:15], v226, s[34:35]
	global_load_dwordx4 v[16:19], v227, s[34:35]
	s_add_u32 s34, s34, 0x4000
	s_addc_u32 s35, s35, 0
	global_load_dwordx4 v[20:23], v226, s[34:35]
	global_load_dwordx4 v[24:27], v227, s[34:35]
	s_add_u32 s34, s34, 0x4000
	s_addc_u32 s35, s35, 0
	global_load_dwordx4 v[28:31], v226, s[34:35]
	global_load_dwordx4 v[32:35], v227, s[34:35]
	s_add_u32 s34, s34, 0x4000
	s_addc_u32 s35, s35, 0
	global_load_dwordx4 v[36:39], v226, s[34:35]
	global_load_dwordx4 v[40:43], v227, s[34:35]
	s_add_u32 s34, s34, 0x4000
	s_addc_u32 s35, s35, 0
	global_load_dwordx4 v[44:47], v226, s[34:35]
	global_load_dwordx4 v[48:51], v227, s[34:35]
	s_add_u32 s34, s34, 0x4000
	s_addc_u32 s35, s35, 0
	global_load_dwordx4 v[52:55], v226, s[34:35]
	global_load_dwordx4 v[56:59], v227, s[34:35]
	s_add_u32 s34, s34, 0x4000
	s_addc_u32 s35, s35, 0
